# v56 + SB/SWA shuffles via permlane swaps
# baseline (speedup 1.0000x reference)
; __device__ __forceinline__ f32x4 mfma16(bf16x8 a, bf16x8 b, f32x4 c) { return __builtin_amdgcn_mfma_f32_16x16x32_bf16(a, b, c, 0, 0, 0); }
; __device__ __forceinline__ void swa_phase(LAS unsigned char* lds, const bf16_t* P, bf16_t* OB, const float* sinks, const float* rel_bias, int G, int cu, int loc) {
;     ...
;         for (int j = 0; j < 9; ++j) mx = fmaxf(mx, fmaxf(fmaxf(S[j][0], S[j][1]), fmaxf(S[j][2], S[j][3])));
;         mx = fmaxf(mx, __shfl_xor(mx, 16)); mx = fmaxf(mx, __shfl_xor(mx, 32));
;         const float mxl = mx * 1.44269504089f;
;         float sum = 0.f;
;         f32x4 O[4];
; #pragma unroll
;         for (int dt = 0; dt < 4; ++dt) O[dt] = (f32x4){0.f, 0.f, 0.f, 0.f};
; #pragma unroll
;         for (int cc = 0; cc < 2; ++cc) {
;             u32x2 vf[16]; tr16(vlane + (unsigned)(cc * 64 * AP * 2), vf);
;             float p[4][4];
; #pragma unroll
;             for (int j = 0; j < 4; ++j)
; #pragma unroll
;                 for (int r = 0; r < 4; ++r) { p[j][r] = __builtin_amdgcn_exp2f(S[4 * cc + j][r] * 1.44269504089f - mxl); sum += p[j][r]; }
; #pragma unroll
;             for (int jj = 0; jj < 2; ++jj) { const bf16x8 pf = pfrag(p, jj);
; #pragma unroll
;                 for (int dt = 0; dt < 4; ++dt) O[dt] = mfma16(vfrag(vf, jj, dt), pf, O[dt]); }
;         }
.LBB0_509:
	v_max_f32_e32 v85, v165, v165
	v_max_f32_e32 v169, v166, v166
	v_max_f32_e32 v85, v169, v85
	v_max_f32_e32 v169, v167, v167
	v_max_f32_e32 v170, v168, v168
	v_max_f32_e32 v169, v170, v169
	s_waitcnt vmcnt(0)
	v_max3_f32 v85, v84, v85, v169
	v_max_f32_e32 v169, v101, v101
	v_max_f32_e32 v170, v100, v100
	v_max_f32_e32 v169, v170, v169
	v_max_f32_e32 v170, v97, v97
	v_max_f32_e32 v171, v96, v96
	v_max_f32_e32 v170, v171, v170
	v_max3_f32 v169, v102, v103, v169
	v_max3_f32 v170, v98, v99, v170
	v_max3_f32 v85, v85, v169, v170
	v_max_f32_e32 v169, v95, v95
	v_max_f32_e32 v170, v94, v94
	v_max_f32_e32 v169, v170, v169
	v_max_f32_e32 v170, v89, v89
	v_max_f32_e32 v171, v88, v88
	v_max_f32_e32 v170, v171, v170
	v_max3_f32 v169, v92, v93, v169
	v_max3_f32 v170, v90, v91, v170
	v_max3_f32 v85, v85, v169, v170
	v_max_f32_e32 v169, v53, v53
	v_max_f32_e32 v170, v52, v52
	v_max_f32_e32 v169, v170, v169
	v_max_f32_e32 v170, v49, v49
	v_max_f32_e32 v171, v48, v48
	v_max_f32_e32 v170, v171, v170
	v_max3_f32 v169, v86, v87, v169
	v_max3_f32 v170, v50, v51, v170
	v_max3_f32 v85, v85, v169, v170
	v_max_f32_e32 v169, v1, v1
	v_max_f32_e32 v170, v0, v0
	v_max_f32_e32 v169, v170, v169
	v_max_f32_e32 v170, v164, v164
	v_max_f32_e32 v171, v163, v163
	v_max_f32_e32 v170, v171, v170
	v_max3_f32 v169, v46, v47, v169
	v_max3_f32 v170, v3, v162, v170
	v_max3_f32 v85, v85, v169, v170
	v_mov_b32_e32 v236, v85
	v_mov_b32_e32 v237, v85
	s_nop 1
	v_permlane16_swap_b32_e32 v236, v237
	v_cndmask_b32_e64 v169, v237, v236, s[98:99]
	s_addk_i32 s97, 0x200
	s_add_u32 s4, s4, 4
	s_addc_u32 s5, s5, 0
	v_lshl_add_u64 v[80:81], v[80:81], 0, s[10:11]
	s_waitcnt lgkmcnt(0)
	v_max_f32_e32 v169, v169, v169
	v_max_f32_e32 v85, v85, v169
	v_mov_b32_e32 v236, v85
	v_mov_b32_e32 v237, v85
	s_nop 1
	v_permlane32_swap_b32_e32 v236, v237
	v_cndmask_b32_e64 v169, v237, v236, s[100:101]
	s_cmpk_eq_i32 s97, 0x800
	s_waitcnt lgkmcnt(0)
	v_max_f32_e32 v169, v169, v169
	v_max_f32_e32 v85, v85, v169
	v_pk_mul_f32 v[84:85], v[84:85], s[8:9] op_sel_hi:[1,0]
	s_nop 0
	v_fma_f32 v166, v166, s8, -v85
	v_exp_f32_e32 v166, v166
	v_fma_f32 v165, v165, s8, -v85
	v_exp_f32_e32 v165, v165
	v_fma_f32 v168, v168, s8, -v85
	v_exp_f32_e32 v188, v168
	v_fma_f32 v167, v167, s8, -v85
	v_exp_f32_e32 v167, v167
	v_fma_f32 v102, v102, s8, -v85
	v_add_f32_e32 v194, 0, v166
	v_exp_f32_e32 v195, v102
	v_fma_f32 v102, v103, s8, -v85
	v_add_f32_e32 v194, v165, v194
	v_exp_f32_e32 v197, v102
	v_fma_f32 v100, v100, s8, -v85
	v_add_f32_e32 v194, v188, v194
	v_exp_f32_e32 v206, v100
	v_fma_f32 v100, v101, s8, -v85
	v_fma_f32 v96, v96, s8, -v85
	ds_read_b64_tr_b16 v[202:203], v104 offset:0
	ds_read_b64_tr_b16 v[204:205], v104 offset:2560
	ds_read_b64_tr_b16 v[198:199], v104 offset:32
	ds_read_b64_tr_b16 v[200:201], v104 offset:2592
	ds_read_b64_tr_b16 v[190:191], v104 offset:64
	ds_read_b64_tr_b16 v[192:193], v104 offset:2624
	ds_read_b64_tr_b16 v[184:185], v104 offset:96
	ds_read_b64_tr_b16 v[186:187], v104 offset:2656
	ds_read_b64_tr_b16 v[180:181], v104 offset:5120
	ds_read_b64_tr_b16 v[182:183], v104 offset:7680
	ds_read_b64_tr_b16 v[176:177], v104 offset:5152
	ds_read_b64_tr_b16 v[178:179], v104 offset:7712
	ds_read_b64_tr_b16 v[172:173], v104 offset:5184
	ds_read_b64_tr_b16 v[174:175], v104 offset:7744
	ds_read_b64_tr_b16 v[168:169], v104 offset:5216
	ds_read_b64_tr_b16 v[170:171], v104 offset:7776
	s_waitcnt lgkmcnt(0)
	v_exp_f32_e32 v207, v100
	v_fma_f32 v98, v98, s8, -v85
	v_exp_f32_e32 v210, v96
	v_fma_f32 v211, v97, s8, -v85
	v_cvt_pk_bf16_f32 v96, v166, v165
	v_cvt_pk_bf16_f32 v97, v188, v167
	v_add_f32_e32 v167, v167, v194
	v_exp_f32_e32 v208, v98
	v_fma_f32 v98, v99, s8, -v85
	v_fma_f32 v92, v92, s8, -v85
	v_add_f32_e32 v167, v195, v167
	v_exp_f32_e32 v209, v98
	v_exp_f32_e32 v166, v92
	v_fma_f32 v92, v93, s8, -v85
	v_add_f32_e32 v167, v197, v167
	v_exp_f32_e32 v188, v92
	v_fma_f32 v92, v94, s8, -v85
	v_add_f32_e32 v167, v206, v167
	v_cvt_pk_bf16_f32 v98, v195, v197
	v_cvt_pk_bf16_f32 v99, v206, v207
	v_exp_f32_e32 v165, v211
	v_mfma_f32_16x16x32_bf16 v[100:103], v[202:205], v[96:99], 0
	v_exp_f32_e32 v202, v92
	v_fma_f32 v92, v95, s8, -v85
	v_add_f32_e32 v167, v207, v167
	v_mfma_f32_16x16x32_bf16 v[198:201], v[198:201], v[96:99], 0
	v_exp_f32_e32 v203, v92
	v_add_f32_e32 v167, v208, v167
	v_add_f32_e32 v167, v209, v167
	v_mfma_f32_16x16x32_bf16 v[190:193], v[190:193], v[96:99], 0
	v_add_f32_e32 v167, v210, v167
	v_fma_f32 v90, v90, s8, -v85
	v_exp_f32_e32 v90, v90
	v_mfma_f32_16x16x32_bf16 v[92:95], v[184:187], v[96:99], 0
	v_cvt_pk_bf16_f32 v96, v208, v209
	v_cvt_pk_bf16_f32 v97, v210, v165
	v_add_f32_e32 v165, v165, v167
	v_cvt_pk_bf16_f32 v98, v166, v188
	v_cvt_pk_bf16_f32 v99, v202, v203
	v_fma_f32 v91, v91, s8, -v85
	v_mfma_f32_16x16x32_bf16 v[100:103], v[180:183], v[96:99], v[100:103]
	v_exp_f32_e32 v91, v91
	v_fma_f32 v88, v88, s8, -v85
	v_exp_f32_e32 v88, v88
	v_mfma_f32_16x16x32_bf16 v[176:179], v[176:179], v[96:99], v[198:201]
	v_fma_f32 v89, v89, s8, -v85
	v_fma_f32 v86, v86, s8, -v85
	v_exp_f32_e32 v194, v86
	v_mfma_f32_16x16x32_bf16 v[172:175], v[172:175], v[96:99], v[190:193]
	v_fma_f32 v86, v87, s8, -v85
	v_exp_f32_e32 v195, v86
	v_fma_f32 v52, v52, s8, -v85
	v_mfma_f32_16x16x32_bf16 v[92:95], v[168:171], v[96:99], v[92:95]
	v_add_f32_e32 v96, v166, v165
	v_add_f32_e32 v96, v188, v96
	v_add_f32_e32 v96, v202, v96
	v_add_f32_e32 v165, v203, v96
	v_exp_f32_e32 v188, v89
	v_add_f32_e32 v165, v90, v165
	v_add_f32_e32 v165, v91, v165
	v_add_f32_e32 v165, v88, v165
	v_exp_f32_e32 v197, v52
	v_fma_f32 v52, v53, s8, -v85
	v_fma_f32 v50, v50, s8, -v85
	v_fma_f32 v48, v48, s8, -v85
	ds_read_b64_tr_b16 v[206:207], v67 offset:0
	ds_read_b64_tr_b16 v[208:209], v67 offset:2560
	ds_read_b64_tr_b16 v[202:203], v67 offset:32
	ds_read_b64_tr_b16 v[204:205], v67 offset:2592
	ds_read_b64_tr_b16 v[198:199], v67 offset:64
	ds_read_b64_tr_b16 v[200:201], v67 offset:2624
	ds_read_b64_tr_b16 v[190:191], v67 offset:96
	ds_read_b64_tr_b16 v[192:193], v67 offset:2656
	ds_read_b64_tr_b16 v[184:185], v67 offset:5120
	ds_read_b64_tr_b16 v[186:187], v67 offset:7680
	ds_read_b64_tr_b16 v[180:181], v67 offset:5152
	ds_read_b64_tr_b16 v[182:183], v67 offset:7712
	ds_read_b64_tr_b16 v[166:167], v67 offset:5184
	ds_read_b64_tr_b16 v[168:169], v67 offset:7744
	ds_read_b64_tr_b16 v[96:97], v67 offset:5216
	ds_read_b64_tr_b16 v[98:99], v67 offset:7776
	s_waitcnt lgkmcnt(0)
; __device__ __forceinline__ unsigned cvt_pk_bf16(float lo, float hi) { unsigned r; asm volatile("v_cvt_pk_bf16_f32 %0, %1, %2" : "=v"(r) : "v"(lo), "v"(hi)); return r; }
; __device__ __forceinline__ f32x4 mfma16(bf16x8 a, bf16x8 b, f32x4 c) { return __builtin_amdgcn_mfma_f32_16x16x32_bf16(a, b, c, 0, 0, 0); }
; __device__ __forceinline__ void swa_phase(LAS unsigned char* lds, const bf16_t* P, bf16_t* OB, const float* sinks, const float* rel_bias, int G, int cu, int loc) {
;     ...
;             for (int j = 0; j < 4; ++j)
; #pragma unroll
;                 for (int r = 0; r < 4; ++r) { p[j][r] = __builtin_amdgcn_exp2f(S[4 * cc + j][r] * 1.44269504089f - mxl); sum += p[j][r]; }
; #pragma unroll
;             for (int jj = 0; jj < 2; ++jj) { const bf16x8 pf = pfrag(p, jj);
; #pragma unroll
;                 for (int dt = 0; dt < 4; ++dt) O[dt] = mfma16(vfrag(vf, jj, dt), pf, O[dt]); }
;         }
;         {
;             u32x2 vf[8]; tr8(vlane + (unsigned)(128 * AP * 2), vf);
;             float p[4];
; #pragma unroll
;             for (int r = 0; r < 4; ++r) { p[r] = __builtin_amdgcn_exp2f(S[8][r] * 1.44269504089f - mxl); sum += p[r]; }
;             u32x4 pw; pw.x = cvt_pk_bf16(p[0], p[1]); pw.y = cvt_pk_bf16(p[2], p[3]); pw.z = 0u; pw.w = 0u;
;             const bf16x8 pf = __builtin_bit_cast(bf16x8, pw);
; #pragma unroll
;             for (int dt = 0; dt < 4; ++dt) { u32x4 wv; wv.x = vf[dt * 2].x; wv.y = vf[dt * 2].y; wv.z = vf[dt * 2 + 1].x; wv.w = vf[dt * 2 + 1].y; O[dt] = mfma16(__builtin_bit_cast(bf16x8, wv), pf, O[dt]); }
;         }
;         sum += __shfl_xor(sum, 16); sum += __shfl_xor(sum, 32);
;         const float inv = 1.0f / (sum + __builtin_amdgcn_exp2f(sink * 1.44269504089f - mxl));
;         bf16_t* op = OB + qtok * D_MODEL + 64 * h + 4 * fq;
; #pragma unroll
;         for (int dt = 0; dt < 4; ++dt) { u32x2 wv; wv.x = cvt_pk_bf16(O[dt][0] * inv, O[dt][1] * inv); wv.y = cvt_pk_bf16(O[dt][2] * inv, O[dt][3] * inv); *(u32x2*)(op + 16 * dt) = wv; }
	v_exp_f32_e32 v210, v52
	v_exp_f32_e32 v211, v50
	v_fma_f32 v50, v51, s8, -v85
	v_exp_f32_e32 v213, v48
	v_cvt_pk_bf16_f32 v48, v90, v91
	v_fma_f32 v46, v46, s8, -v85
	v_add_f32_e32 v90, v188, v165
	v_exp_f32_e32 v212, v50
	v_fma_f32 v52, v49, s8, -v85
	v_cvt_pk_bf16_f32 v49, v88, v188
	v_cvt_pk_bf16_f32 v50, v194, v195
	v_cvt_pk_bf16_f32 v51, v197, v210
	v_add_f32_e32 v90, v194, v90
	v_mfma_f32_16x16x32_bf16 v[86:89], v[206:209], v[48:51], v[100:103]
	v_exp_f32_e32 v207, v46
	v_fma_f32 v46, v47, s8, -v85
	v_exp_f32_e32 v206, v52
	v_mfma_f32_16x16x32_bf16 v[100:103], v[202:205], v[48:51], v[176:179]
	v_fma_f32 v0, v0, s8, -v85
	v_exp_f32_e32 v0, v0
	v_fma_f32 v1, v1, s8, -v85
	v_exp_f32_e32 v176, v46
	v_mfma_f32_16x16x32_bf16 v[170:173], v[198:201], v[48:51], v[172:175]
	v_exp_f32_e32 v1, v1
	v_fma_f32 v3, v3, s8, -v85
	v_sub_f32_e32 v84, v84, v85
	v_mfma_f32_16x16x32_bf16 v[46:49], v[190:193], v[48:51], v[92:95]
	v_cvt_pk_bf16_f32 v50, v211, v212
	v_cvt_pk_bf16_f32 v51, v213, v206
	v_cvt_pk_bf16_f32 v52, v207, v176
	v_cvt_pk_bf16_f32 v53, v0, v1
	v_exp_f32_e32 v84, v84
	s_nop 1
	v_add_f32_e32 v94, v195, v90
	v_add_f32_e32 v94, v197, v94
	v_add_f32_e32 v94, v210, v94
	v_add_f32_e32 v94, v211, v94
	v_add_f32_e32 v94, v212, v94
	v_add_f32_e32 v94, v213, v94
	v_add_f32_e32 v94, v206, v94
	v_mfma_f32_16x16x32_bf16 v[86:89], v[184:187], v[50:53], v[86:89]
	v_mfma_f32_16x16x32_bf16 v[90:93], v[180:183], v[50:53], v[100:103]
	v_mfma_f32_16x16x32_bf16 v[100:103], v[166:169], v[50:53], v[170:173]
	v_mfma_f32_16x16x32_bf16 v[46:49], v[96:99], v[50:53], v[46:49]
	v_add_f32_e32 v50, v207, v94
	v_exp_f32_e32 v98, v3
	v_fma_f32 v3, v162, s8, -v85
	v_add_f32_e32 v50, v176, v50
	v_exp_f32_e32 v99, v3
	v_fma_f32 v3, v163, s8, -v85
	v_add_f32_e32 v0, v0, v50
	v_exp_f32_e32 v170, v3
	v_fma_f32 v3, v164, s8, -v85
	v_exp_f32_e32 v171, v3
	v_add_f32_e32 v172, v1, v0
	ds_read_b64_tr_b16 v[166:167], v107 offset:0
	ds_read_b64_tr_b16 v[168:169], v107 offset:2560
	ds_read_b64_tr_b16 v[162:163], v107 offset:32
	ds_read_b64_tr_b16 v[164:165], v107 offset:2592
	ds_read_b64_tr_b16 v[94:95], v107 offset:64
	ds_read_b64_tr_b16 v[96:97], v107 offset:2624
	ds_read_b64_tr_b16 v[50:51], v107 offset:96
	ds_read_b64_tr_b16 v[52:53], v107 offset:2656
	s_waitcnt lgkmcnt(0)
	v_cvt_pk_bf16_f32 v0, v98, v99
	v_add_f32_e32 v98, v98, v172
	v_add_f32_e32 v98, v99, v98
	v_add_f32_e32 v98, v170, v98
	v_add_f32_e32 v98, v171, v98
	v_mov_b32_e32 v236, v98
	v_mov_b32_e32 v237, v98
	s_nop 1
	v_permlane16_swap_b32_e32 v236, v237
	v_cndmask_b32_e64 v99, v237, v236, s[98:99]
	v_mov_b32_e32 v3, v2
	v_cvt_pk_bf16_f32 v1, v170, v171
	s_waitcnt lgkmcnt(0)
	v_add_f32_e32 v98, v98, v99
	v_mov_b32_e32 v236, v98
	v_mov_b32_e32 v237, v98
	s_nop 1
	v_permlane32_swap_b32_e32 v236, v237
	v_cndmask_b32_e64 v99, v237, v236, s[100:101]
	v_mfma_f32_16x16x32_bf16 v[86:89], v[166:169], v[0:3], v[86:89]
	s_waitcnt lgkmcnt(0)
	v_add_f32_e32 v85, v98, v99
	v_add_f32_e32 v84, v84, v85
	v_div_scale_f32 v85, s[12:13], v84, v84, 1.0
	v_rcp_f32_e32 v98, v85
	v_mfma_f32_16x16x32_bf16 v[90:93], v[162:165], v[0:3], v[90:93]
	v_mfma_f32_16x16x32_bf16 v[94:97], v[94:97], v[0:3], v[100:103]
	v_mfma_f32_16x16x32_bf16 v[46:49], v[50:53], v[0:3], v[46:49]
	v_fma_f32 v0, -v85, v98, 1.0
	v_fmac_f32_e32 v98, v0, v98
	v_div_scale_f32 v0, vcc, 1.0, v84, 1.0
	v_mul_f32_e32 v1, v0, v98
	v_fma_f32 v3, -v85, v1, v0
	v_fmac_f32_e32 v1, v3, v98
	v_fma_f32 v0, -v85, v1, v0
	v_div_fmas_f32 v0, v0, v98, v1
	v_div_fixup_f32 v3, v0, v84, 1.0
	v_mul_f32_e32 v0, v86, v3
	v_mul_f32_e32 v1, v87, v3
	v_cvt_pk_bf16_f32 v0, v0, v1
	v_mul_f32_e32 v1, v88, v3
	v_mul_f32_e32 v50, v89, v3
	v_cvt_pk_bf16_f32 v1, v1, v50
	global_store_dwordx2 v[82:83], v[0:1], off offset:-64
	v_mul_f32_e32 v0, v90, v3
	v_mul_f32_e32 v1, v91, v3
	v_cvt_pk_bf16_f32 v0, v0, v1
	v_mul_f32_e32 v1, v92, v3
	v_mul_f32_e32 v50, v93, v3
	v_cvt_pk_bf16_f32 v1, v1, v50
	global_store_dwordx2 v[82:83], v[0:1], off offset:-32
	v_mul_f32_e32 v0, v94, v3
	v_mul_f32_e32 v1, v95, v3
	v_cvt_pk_bf16_f32 v0, v0, v1
	v_mul_f32_e32 v1, v96, v3
	v_mul_f32_e32 v50, v97, v3
	v_cvt_pk_bf16_f32 v1, v1, v50
	global_store_dwordx2 v[82:83], v[0:1], off
	v_mul_f32_e32 v0, v46, v3
	v_mul_f32_e32 v1, v47, v3
	v_cvt_pk_bf16_f32 v0, v0, v1
	v_mul_f32_e32 v1, v48, v3
	v_mul_f32_e32 v3, v49, v3
	v_mov_b64_e32 v[52:53], v[44:45]
	v_mov_b64_e32 v[48:49], v[40:41]
	v_cvt_pk_bf16_f32 v1, v1, v3
	global_store_dwordx2 v[82:83], v[0:1], off offset:32
	v_lshl_add_u64 v[82:83], v[82:83], 0, s[10:11]
	v_mov_b64_e32 v[50:51], v[42:43]
	v_mov_b64_e32 v[46:47], v[38:39]
	s_cbranch_scc1 .LBB0_492

; #define LAS __attribute__((address_space(3)))
; __device__ __forceinline__ f32x4 mfma16(bf16x8 a, bf16x8 b, f32x4 c) { return __builtin_amdgcn_mfma_f32_16x16x32_bf16(a, b, c, 0, 0, 0); }
; template <bool DIAG>
; __device__ __forceinline__ void sb_step(const LAS bf16_t* Kt, unsigned vaddr, int kbase, int qpos, bf16x8 q0, bf16x8 q1, float& carry, f32x4 (&O)[4], int fr, int fq) {
;     ...
;     for (int j = 0; j < 2; ++j) {
;         const LAS bf16_t* kp = Kt + (16 * j + fr) * AP + 8 * fq;
;         f32x4 t = (f32x4){0.f, 0.f, 0.f, 0.f};
;         t = mfma16(*(const LAS bf16x8*)kp, q0, t); t = mfma16(*(const LAS bf16x8*)(kp + 32), q1, t); s[j] = t;
;     }
;     u32x2 vf[8]; tr8(vaddr, vf);
;     f32x2 sg[4], om[4];
; #pragma unroll
;     for (int r = 0; r < 4; ++r) {
;         f32x2 t = (f32x2){s[0][r], s[1][r]} * (-0.125f * 1.44269504089f);
;         t.x = __builtin_amdgcn_fmed3f(t.x, -115.4f, 115.4f); t.y = __builtin_amdgcn_fmed3f(t.y, -115.4f, 115.4f);
;         f32x2 ex; ex.x = __builtin_amdgcn_exp2f(t.x); ex.y = __builtin_amdgcn_exp2f(t.y);
;         const f32x2 d = ex + 1.0f; f32x2 rc; rc.x = __builtin_amdgcn_rcpf(d.x); rc.y = __builtin_amdgcn_rcpf(d.y);
;         f32x2 o = ex * rc;
;         if (DIAG) { const int key = kbase + 4 * fq + r; const bool c0 = key < qpos, c1 = key + 16 < qpos;
;             rc.x = c0 ? rc.x : 0.f; o.x = c0 ? o.x : 1.f; rc.y = c1 ? rc.y : 0.f; o.y = c1 ? o.y : 1.f; }
;         sg[r] = rc; om[r] = o;
;     }
;     const f32x2 g = (om[0] * om[1]) * (om[2] * om[3]);
;     f32x2 x1; x1.x = __shfl_xor(g.x, 16); x1.y = __shfl_xor(g.y, 16);
;     const f32x2 p1 = g * x1;
;     f32x2 x2; x2.x = __shfl_xor(p1.x, 32); x2.y = __shfl_xor(p1.y, 32);
.LBB0_558:
	s_waitcnt lgkmcnt(3)
	ds_read_b128 v[94:97], v125
	s_waitcnt lgkmcnt(3)
	ds_read_b128 v[98:101], v125 offset:64
	s_waitcnt lgkmcnt(3)
	ds_read_b128 v[102:105], v125 offset:2560
	s_waitcnt lgkmcnt(3)
	ds_read_b128 v[90:93], v125 offset:2624
	s_cmp_lt_i32 s57, s26
	s_mov_b64 s[0:1], -1
	s_cbranch_scc1 .LBB0_566
	s_waitcnt lgkmcnt(3)
	v_mfma_f32_16x16x32_bf16 v[2:5], v[94:97], v[62:65], 0
	v_add_u32_e32 v12, -3, v123
	v_cmp_lt_i32_e64 s[10:11], v12, v126
	v_add_u32_e32 v12, -2, v123
	s_waitcnt lgkmcnt(1)
	v_mfma_f32_16x16x32_bf16 v[6:9], v[102:105], v[62:65], 0
	v_cmp_lt_i32_e64 s[14:15], v12, v126
	v_cmp_lt_i32_e64 s[20:21], v123, v126
	v_mfma_f32_16x16x32_bf16 v[2:5], v[98:101], v[66:69], v[2:5]
	s_waitcnt lgkmcnt(0)
	v_mfma_f32_16x16x32_bf16 v[6:9], v[90:93], v[66:69], v[6:9]
	s_nop 5
	v_mov_b32_e32 v10, v2
	s_nop 0
	v_mov_b32_e32 v11, v6
	v_pk_mul_f32 v[10:11], v[10:11], s[28:29] op_sel_hi:[1,0]
	v_mov_b32_e32 v6, v3
	v_med3_f32 v1, v10, s45, v119
	v_med3_f32 v2, v11, s45, v119
	v_exp_f32_e32 v10, v1
	v_exp_f32_e32 v11, v2
	v_pk_mul_f32 v[2:3], v[6:7], s[28:29] op_sel_hi:[1,0]
	v_pk_add_f32 v[6:7], v[10:11], 1.0 op_sel_hi:[1,0]
	v_med3_f32 v1, v2, s45, v119
	v_med3_f32 v3, v3, s45, v119
	v_rcp_f32_e32 v128, v6
	v_rcp_f32_e32 v129, v7
	v_exp_f32_e32 v2, v1
	v_exp_f32_e32 v3, v3
	v_subrev_u32_e32 v1, 19, v123
	v_pk_mul_f32 v[6:7], v[10:11], v[128:129]
	v_cmp_lt_i32_e32 vcc, v1, v126
	v_pk_add_f32 v[10:11], v[2:3], 1.0 op_sel_hi:[1,0]
	v_subrev_u32_e32 v1, 18, v123
	v_rcp_f32_e32 v132, v10
	v_rcp_f32_e32 v133, v11
	v_mov_b32_e32 v10, v4
	v_mov_b32_e32 v11, v8
	v_pk_mul_f32 v[10:11], v[10:11], s[28:29] op_sel_hi:[1,0]
	v_pk_mul_f32 v[2:3], v[2:3], v[132:133]
	v_med3_f32 v4, v10, s45, v119
	v_med3_f32 v8, v11, s45, v119
	v_exp_f32_e32 v10, v4
	v_exp_f32_e32 v11, v8
	v_cmp_lt_i32_e64 s[12:13], v1, v126
	v_cndmask_b32_e64 v135, 1.0, v3, s[14:15]
	v_mov_b32_e32 v8, v5
	v_cndmask_b32_e64 v134, 1.0, v2, s[12:13]
	v_pk_add_f32 v[2:3], v[10:11], 1.0 op_sel_hi:[1,0]
	v_cndmask_b32_e32 v6, 1.0, v6, vcc
	v_rcp_f32_e32 v136, v2
	v_rcp_f32_e32 v137, v3
	v_pk_mul_f32 v[2:3], v[8:9], s[28:29] op_sel_hi:[1,0]
	v_cndmask_b32_e64 v7, 1.0, v7, s[10:11]
	v_med3_f32 v1, v2, s45, v119
	v_med3_f32 v3, v3, s45, v119
	v_exp_f32_e32 v2, v1
	v_exp_f32_e32 v3, v3
	v_subrev_u32_e32 v1, 17, v123
	v_pk_mul_f32 v[4:5], v[10:11], v[136:137]
	v_add_u32_e32 v10, -1, v123
	v_pk_add_f32 v[8:9], v[2:3], 1.0 op_sel_hi:[1,0]
	v_cmp_lt_i32_e64 s[0:1], v1, v126
	v_rcp_f32_e32 v142, v8
	v_rcp_f32_e32 v143, v9
	v_add_u32_e32 v1, -16, v123
	v_cmp_lt_i32_e64 s[16:17], v10, v126
	v_cmp_lt_i32_e64 s[18:19], v1, v126
	v_pk_mul_f32 v[2:3], v[2:3], v[142:143]
	v_cndmask_b32_e64 v138, 1.0, v4, s[0:1]
	v_cndmask_b32_e64 v139, 1.0, v5, s[16:17]
	v_cndmask_b32_e64 v140, 1.0, v2, s[18:19]
	v_cndmask_b32_e64 v141, 1.0, v3, s[20:21]
	v_pk_mul_f32 v[2:3], v[6:7], v[134:135]
	v_pk_mul_f32 v[4:5], v[138:139], v[140:141]
	v_xor_b32_e32 v1, 16, v165
	v_pk_mul_f32 v[2:3], v[2:3], v[4:5]
	v_and_b32_e32 v4, 64, v165
	v_add_u32_e32 v4, 64, v4
	v_cmp_lt_i32_e64 s[22:23], v1, v4
	s_nop 1
	v_cndmask_b32_e64 v1, v165, v1, s[22:23]
	v_lshlrev_b32_e32 v1, 2, v1
	v_mov_b32_e32 v236, v2
	v_mov_b32_e32 v237, v2
	s_nop 1
	v_permlane16_swap_b32_e32 v236, v237
	v_cndmask_b32_e64 v150, v237, v236, s[98:99]
	v_mov_b32_e32 v236, v3
	v_mov_b32_e32 v237, v3
	s_nop 1
	v_permlane16_swap_b32_e32 v236, v237
	v_cndmask_b32_e64 v151, v237, v236, s[98:99]
	v_xor_b32_e32 v1, 32, v165
	v_cmp_lt_i32_e64 s[22:23], v1, v4
	s_waitcnt lgkmcnt(0)
	v_pk_mul_f32 v[146:147], v[2:3], v[150:151]
	v_cndmask_b32_e64 v1, v165, v1, s[22:23]
	v_lshlrev_b32_e32 v1, 2, v1
	v_mov_b32_e32 v236, v146
	v_mov_b32_e32 v237, v146
	s_nop 1
	v_permlane32_swap_b32_e32 v236, v237
	v_cndmask_b32_e64 v148, v237, v236, s[100:101]
	v_mov_b32_e32 v236, v147
	v_mov_b32_e32 v237, v147
	s_nop 1
	v_permlane32_swap_b32_e32 v236, v237
	v_cndmask_b32_e64 v149, v237, v236, s[100:101]
	ds_read_b64_tr_b16 v[2:3], v127 offset:0
	ds_read_b64_tr_b16 v[4:5], v127 offset:2560
	ds_read_b64_tr_b16 v[6:7], v127 offset:32
	ds_read_b64_tr_b16 v[8:9], v127 offset:2592
	ds_read_b64_tr_b16 v[10:11], v127 offset:64
	ds_read_b64_tr_b16 v[12:13], v127 offset:2624
	ds_read_b64_tr_b16 v[14:15], v127 offset:96
	ds_read_b64_tr_b16 v[16:17], v127 offset:2656
	s_waitcnt lgkmcnt(0)
	v_cmp_lt_i32_e64 s[22:23], 0, v156
	s_and_saveexec_b64 s[4:5], s[22:23]
	s_xor_b64 s[4:5], exec, s[4:5]
	s_cbranch_execz .LBB0_563
	v_cmp_ne_u32_e64 s[22:23], 1, v156
	s_waitcnt lgkmcnt(0)
	v_mov_b64_e32 v[144:145], v[148:149]
	s_and_saveexec_b64 s[34:35], s[22:23]
	v_cndmask_b32_e64 v145, 1.0, v151, s[6:7]
	v_cndmask_b32_e64 v144, 1.0, v150, s[6:7]
	s_or_b64 exec, exec, s[34:35]

; #define LAS __attribute__((address_space(3)))
; __device__ __forceinline__ f32x4 mfma16(bf16x8 a, bf16x8 b, f32x4 c) { return __builtin_amdgcn_mfma_f32_16x16x32_bf16(a, b, c, 0, 0, 0); }
; template <bool DIAG>
; __device__ __forceinline__ void sb_step(const LAS bf16_t* Kt, unsigned vaddr, int kbase, int qpos, bf16x8 q0, bf16x8 q1, float& carry, f32x4 (&O)[4], int fr, int fq) {
;     ...
;     for (int j = 0; j < 2; ++j) {
;         const LAS bf16_t* kp = Kt + (16 * j + fr) * AP + 8 * fq;
;         f32x4 t = (f32x4){0.f, 0.f, 0.f, 0.f};
;         t = mfma16(*(const LAS bf16x8*)kp, q0, t); t = mfma16(*(const LAS bf16x8*)(kp + 32), q1, t); s[j] = t;
;     }
;     u32x2 vf[8]; tr8(vaddr, vf);
;     f32x2 sg[4], om[4];
; #pragma unroll
;     for (int r = 0; r < 4; ++r) {
;         f32x2 t = (f32x2){s[0][r], s[1][r]} * (-0.125f * 1.44269504089f);
;         t.x = __builtin_amdgcn_fmed3f(t.x, -115.4f, 115.4f); t.y = __builtin_amdgcn_fmed3f(t.y, -115.4f, 115.4f);
;         f32x2 ex; ex.x = __builtin_amdgcn_exp2f(t.x); ex.y = __builtin_amdgcn_exp2f(t.y);
;         const f32x2 d = ex + 1.0f; f32x2 rc; rc.x = __builtin_amdgcn_rcpf(d.x); rc.y = __builtin_amdgcn_rcpf(d.y);
;         f32x2 o = ex * rc;
;         if (DIAG) { const int key = kbase + 4 * fq + r; const bool c0 = key < qpos, c1 = key + 16 < qpos;
;             rc.x = c0 ? rc.x : 0.f; o.x = c0 ? o.x : 1.f; rc.y = c1 ? rc.y : 0.f; o.y = c1 ? o.y : 1.f; }
;         sg[r] = rc; om[r] = o;
;     }
;     const f32x2 g = (om[0] * om[1]) * (om[2] * om[3]);
;     f32x2 x1; x1.x = __shfl_xor(g.x, 16); x1.y = __shfl_xor(g.y, 16);
;     const f32x2 p1 = g * x1;
;     f32x2 x2; x2.x = __shfl_xor(p1.x, 32); x2.y = __shfl_xor(p1.y, 32);
.LBB0_566:
	s_and_b64 vcc, exec, s[0:1]
	s_cbranch_vccz .LBB0_574
	s_waitcnt lgkmcnt(3)
	v_mfma_f32_16x16x32_bf16 v[2:5], v[94:97], v[62:65], 0
	s_waitcnt lgkmcnt(1)
	v_mfma_f32_16x16x32_bf16 v[6:9], v[102:105], v[62:65], 0
	v_mfma_f32_16x16x32_bf16 v[2:5], v[98:101], v[66:69], v[2:5]
	s_waitcnt lgkmcnt(0)
	v_mfma_f32_16x16x32_bf16 v[6:9], v[90:93], v[66:69], v[6:9]
	s_nop 5
	v_mov_b32_e32 v10, v2
	s_nop 0
	v_mov_b32_e32 v11, v6
	v_pk_mul_f32 v[10:11], v[10:11], s[28:29] op_sel_hi:[1,0]
	v_mov_b32_e32 v6, v3
	v_med3_f32 v2, v11, s45, v119
	v_med3_f32 v1, v10, s45, v119
	v_exp_f32_e32 v11, v2
	v_pk_mul_f32 v[2:3], v[6:7], s[28:29] op_sel_hi:[1,0]
	v_exp_f32_e32 v10, v1
	v_med3_f32 v1, v2, s45, v119
	v_med3_f32 v3, v3, s45, v119
	v_exp_f32_e32 v2, v1
	v_exp_f32_e32 v3, v3
	v_pk_add_f32 v[6:7], v[10:11], 1.0 op_sel_hi:[1,0]
	s_nop 0
	v_rcp_f32_e32 v90, v6
	v_rcp_f32_e32 v91, v7
	v_pk_add_f32 v[6:7], v[2:3], 1.0 op_sel_hi:[1,0]
	s_nop 0
	v_rcp_f32_e32 v92, v6
	v_rcp_f32_e32 v93, v7
	v_mov_b32_e32 v6, v4
	v_mov_b32_e32 v7, v8
	v_pk_mul_f32 v[6:7], v[6:7], s[28:29] op_sel_hi:[1,0]
	v_mov_b32_e32 v8, v5
	v_med3_f32 v4, v7, s45, v119
	v_med3_f32 v1, v6, s45, v119
	v_exp_f32_e32 v7, v4
	v_pk_mul_f32 v[4:5], v[8:9], s[28:29] op_sel_hi:[1,0]
	v_exp_f32_e32 v6, v1
	v_med3_f32 v1, v4, s45, v119
	v_med3_f32 v5, v5, s45, v119
	v_exp_f32_e32 v4, v1
	v_exp_f32_e32 v5, v5
	v_pk_add_f32 v[8:9], v[6:7], 1.0 op_sel_hi:[1,0]
	v_pk_mul_f32 v[96:97], v[2:3], v[92:93]
	v_rcp_f32_e32 v94, v8
	v_rcp_f32_e32 v95, v9
	v_pk_add_f32 v[8:9], v[4:5], 1.0 op_sel_hi:[1,0]
	v_xor_b32_e32 v1, 16, v165
	v_rcp_f32_e32 v100, v8
	v_rcp_f32_e32 v101, v9
	v_pk_mul_f32 v[8:9], v[10:11], v[90:91]
	v_pk_mul_f32 v[98:99], v[6:7], v[94:95]
	v_pk_mul_f32 v[2:3], v[8:9], v[96:97]
	v_pk_mul_f32 v[102:103], v[4:5], v[100:101]
	s_nop 0
	v_pk_mul_f32 v[4:5], v[98:99], v[102:103]
	s_nop 0
	v_pk_mul_f32 v[2:3], v[2:3], v[4:5]
	v_and_b32_e32 v4, 64, v165
	v_add_u32_e32 v4, 64, v4
	v_cmp_lt_i32_e32 vcc, v1, v4
	s_nop 1
	v_cndmask_b32_e32 v1, v165, v1, vcc
	v_lshlrev_b32_e32 v1, 2, v1
	v_mov_b32_e32 v236, v2
	v_mov_b32_e32 v237, v2
	s_nop 1
	v_permlane16_swap_b32_e32 v236, v237
	v_cndmask_b32_e64 v132, v237, v236, s[98:99]
	v_mov_b32_e32 v236, v3
	v_mov_b32_e32 v237, v3
	s_nop 1
	v_permlane16_swap_b32_e32 v236, v237
	v_cndmask_b32_e64 v133, v237, v236, s[98:99]
	v_xor_b32_e32 v1, 32, v165
	v_cmp_lt_i32_e32 vcc, v1, v4
	s_waitcnt lgkmcnt(0)
	v_pk_mul_f32 v[104:105], v[2:3], v[132:133]
	v_cndmask_b32_e32 v1, v165, v1, vcc
	v_lshlrev_b32_e32 v1, 2, v1
	v_mov_b32_e32 v236, v104
	v_mov_b32_e32 v237, v104
	s_nop 1
	v_permlane32_swap_b32_e32 v236, v237
	v_cndmask_b32_e64 v128, v237, v236, s[100:101]
	v_mov_b32_e32 v236, v105
	v_mov_b32_e32 v237, v105
	s_nop 1
	v_permlane32_swap_b32_e32 v236, v237
	v_cndmask_b32_e64 v129, v237, v236, s[100:101]
	ds_read_b64_tr_b16 v[2:3], v127 offset:0
	ds_read_b64_tr_b16 v[4:5], v127 offset:2560
	ds_read_b64_tr_b16 v[6:7], v127 offset:32
	ds_read_b64_tr_b16 v[8:9], v127 offset:2592
	ds_read_b64_tr_b16 v[10:11], v127 offset:64
	ds_read_b64_tr_b16 v[12:13], v127 offset:2624
	ds_read_b64_tr_b16 v[14:15], v127 offset:96
	ds_read_b64_tr_b16 v[16:17], v127 offset:2656
	s_waitcnt lgkmcnt(0)
	v_cmp_lt_i32_e32 vcc, 0, v156
	s_and_saveexec_b64 s[0:1], vcc
	s_xor_b64 s[0:1], exec, s[0:1]
	s_cbranch_execz .LBB0_571
	v_cmp_ne_u32_e32 vcc, 1, v156
	s_waitcnt lgkmcnt(0)
	v_mov_b64_e32 v[134:135], v[128:129]
	s_and_saveexec_b64 s[4:5], vcc
	v_cndmask_b32_e64 v135, 1.0, v133, s[6:7]
	v_cndmask_b32_e64 v134, 1.0, v132, s[6:7]
	s_or_b64 exec, exec, s[4:5]

; #define LAS __attribute__((address_space(3)))
; template <bool DIAG>
; __device__ __forceinline__ void sb_step(const LAS bf16_t* Kt, unsigned vaddr, int kbase, int qpos, bf16x8 q0, bf16x8 q1, float& carry, f32x4 (&O)[4], int fr, int fq) {
;     f32x4 s[2];
; #pragma unroll
;     for (int j = 0; j < 2; ++j) {
;         const LAS bf16_t* kp = Kt + (16 * j + fr) * AP + 8 * fq;
;         f32x4 t = (f32x4){0.f, 0.f, 0.f, 0.f};
;         t = mfma16(*(const LAS bf16x8*)kp, q0, t); t = mfma16(*(const LAS bf16x8*)(kp + 32), q1, t); s[j] = t;
;     }
;     u32x2 vf[8]; tr8(vaddr, vf);
;     f32x2 sg[4], om[4];
; #pragma unroll
;     for (int r = 0; r < 4; ++r) {
;         f32x2 t = (f32x2){s[0][r], s[1][r]} * (-0.125f * 1.44269504089f);
;         t.x = __builtin_amdgcn_fmed3f(t.x, -115.4f, 115.4f); t.y = __builtin_amdgcn_fmed3f(t.y, -115.4f, 115.4f);
;         f32x2 ex; ex.x = __builtin_amdgcn_exp2f(t.x); ex.y = __builtin_amdgcn_exp2f(t.y);
;         const f32x2 d = ex + 1.0f; f32x2 rc; rc.x = __builtin_amdgcn_rcpf(d.x); rc.y = __builtin_amdgcn_rcpf(d.y);
;         f32x2 o = ex * rc;
;         if (DIAG) { const int key = kbase + 4 * fq + r; const bool c0 = key < qpos, c1 = key + 16 < qpos;
;             rc.x = c0 ? rc.x : 0.f; o.x = c0 ? o.x : 1.f; rc.y = c1 ? rc.y : 0.f; o.y = c1 ? o.y : 1.f; }
;         sg[r] = rc; om[r] = o;
;     }
;     const f32x2 g = (om[0] * om[1]) * (om[2] * om[3]);
;     f32x2 x1; x1.x = __shfl_xor(g.x, 16); x1.y = __shfl_xor(g.y, 16);
;     const f32x2 p1 = g * x1;
;     f32x2 x2; x2.x = __shfl_xor(p1.x, 32); x2.y = __shfl_xor(p1.y, 32);
;     const f32x2 T = p1 * x2;
;     const f32x2 one = (f32x2){1.0f, 1.0f};
; __device__ __forceinline__ void sb_phase(LAS unsigned char* lds, const bf16_t* P, bf16_t* OB, int G, int cu, int loc) {
;     ...
;                 { const int key = tid >> 3, dp = tid & 7;
;                   const bf16_t* src = P + (tokb + 64 * kt + key) * PITCH + C_KB + 64 * u.h + 8 * dp;
;                   const u32x4 kv = *(const u32x4*)src, vv = *(const u32x4*)(src + (C_VB - C_KB));
;                   *(LAS u32x4*)(Ks + key * AP + 8 * dp) = kv; *(LAS u32x4*)(Vs + key * AP + 8 * dp) = vv; }
;                 __syncthreads();
;                 if (!done) { sb_step<false>(Ks + 32 * AP, vlane + (unsigned)(32 * AP * 2), 64 * kt + 32, qpos, q0, q1, carry, O, fr, fq); done = __all(carry < SB_DONE) != 0; }
.LBB0_583:
	v_lshl_add_u64 v[90:91], v[130:131], 0, s[26:27]
	v_mad_u64_u32 v[94:95], s[12:13], v90, s44, v[132:133]
	v_mad_i32_i24 v95, v91, s44, v95
	global_load_dwordx4 v[90:93], v[94:95], off offset:2560
	s_nop 0
	global_load_dwordx4 v[94:97], v[94:95], off offset:3584
	s_xor_b64 s[10:11], s[10:11], -1
	s_andn2_b64 vcc, exec, s[10:11]
	s_mov_b64 s[10:11], -1
	s_waitcnt vmcnt(1)
	ds_write_b128 v162, v[90:93]
	s_waitcnt vmcnt(0)
	ds_write_b128 v162, v[94:97] offset:51200
	s_waitcnt lgkmcnt(0)
	s_barrier
	s_cbranch_vccnz .LBB0_582
	ds_read_b128 v[90:93], v166 offset:5120
	ds_read_b128 v[94:97], v166 offset:5184
	ds_read_b128 v[98:101], v166 offset:7680
	ds_read_b128 v[102:105], v166 offset:7744
	s_waitcnt lgkmcnt(3)
	v_mfma_f32_16x16x32_bf16 v[90:93], v[90:93], v[62:65], 0
	s_waitcnt lgkmcnt(1)
	v_mfma_f32_16x16x32_bf16 v[98:101], v[98:101], v[62:65], 0
	v_mfma_f32_16x16x32_bf16 v[90:93], v[94:97], v[66:69], v[90:93]
	s_waitcnt lgkmcnt(0)
	v_mfma_f32_16x16x32_bf16 v[94:97], v[102:105], v[66:69], v[98:101]
	s_nop 5
	v_mov_b32_e32 v98, v90
	s_nop 0
	v_mov_b32_e32 v99, v94
	v_mov_b32_e32 v94, v91
	v_pk_mul_f32 v[90:91], v[98:99], s[28:29] op_sel_hi:[1,0]
	v_pk_mul_f32 v[94:95], v[94:95], s[28:29] op_sel_hi:[1,0]
	v_med3_f32 v1, v90, s45, v119
	v_med3_f32 v91, v91, s45, v119
	v_exp_f32_e32 v90, v1
	v_exp_f32_e32 v91, v91
	v_med3_f32 v94, v94, s45, v119
	v_med3_f32 v95, v95, s45, v119
	v_exp_f32_e32 v94, v94
	v_pk_add_f32 v[98:99], v[90:91], 1.0 op_sel_hi:[1,0]
	v_exp_f32_e32 v95, v95
	v_rcp_f32_e32 v134, v98
	v_rcp_f32_e32 v135, v99
	v_mov_b32_e32 v98, v92
	v_mov_b32_e32 v99, v96
	v_pk_mul_f32 v[98:99], v[98:99], s[28:29] op_sel_hi:[1,0]
	v_mov_b32_e32 v96, v93
	v_med3_f32 v92, v99, s45, v119
	v_med3_f32 v1, v98, s45, v119
	v_exp_f32_e32 v99, v92
	v_pk_mul_f32 v[92:93], v[96:97], s[28:29] op_sel_hi:[1,0]
	v_exp_f32_e32 v98, v1
	v_med3_f32 v1, v92, s45, v119
	v_med3_f32 v93, v93, s45, v119
	v_exp_f32_e32 v92, v1
	v_exp_f32_e32 v93, v93
	v_pk_add_f32 v[96:97], v[98:99], 1.0 op_sel_hi:[1,0]
	v_pk_add_f32 v[100:101], v[94:95], 1.0 op_sel_hi:[1,0]
	v_rcp_f32_e32 v138, v96
	v_rcp_f32_e32 v139, v97
	v_pk_add_f32 v[96:97], v[92:93], 1.0 op_sel_hi:[1,0]
	v_rcp_f32_e32 v136, v100
	v_rcp_f32_e32 v137, v101
	v_rcp_f32_e32 v144, v96
	v_rcp_f32_e32 v145, v97
	v_pk_mul_f32 v[90:91], v[90:91], v[134:135]
	v_pk_mul_f32 v[140:141], v[94:95], v[136:137]
	v_pk_mul_f32 v[142:143], v[98:99], v[138:139]
	v_pk_mul_f32 v[146:147], v[92:93], v[144:145]
	v_pk_mul_f32 v[90:91], v[90:91], v[140:141]
	v_pk_mul_f32 v[92:93], v[142:143], v[146:147]
	v_xor_b32_e32 v1, 16, v165
	v_pk_mul_f32 v[90:91], v[90:91], v[92:93]
	v_and_b32_e32 v92, 64, v165
	v_add_u32_e32 v92, 64, v92
	v_cmp_lt_i32_e32 vcc, v1, v92
	s_nop 1
	v_cndmask_b32_e32 v1, v165, v1, vcc
	v_lshlrev_b32_e32 v1, 2, v1
	v_mov_b32_e32 v236, v90
	v_mov_b32_e32 v237, v90
	s_nop 1
	v_permlane16_swap_b32_e32 v236, v237
	v_cndmask_b32_e64 v152, v237, v236, s[98:99]
	v_mov_b32_e32 v236, v91
	v_mov_b32_e32 v237, v91
	s_nop 1
	v_permlane16_swap_b32_e32 v236, v237
	v_cndmask_b32_e64 v153, v237, v236, s[98:99]
	s_waitcnt lgkmcnt(0)
	v_pk_mul_f32 v[148:149], v[90:91], v[152:153]
	v_xor_b32_e32 v90, 32, v165
	v_cmp_lt_i32_e32 vcc, v90, v92
	s_nop 1
	v_cndmask_b32_e32 v90, v165, v90, vcc
	v_lshlrev_b32_e32 v123, 2, v90
	v_mov_b32_e32 v236, v148
	v_mov_b32_e32 v237, v148
	s_nop 1
	v_permlane32_swap_b32_e32 v236, v237
	v_cndmask_b32_e64 v150, v237, v236, s[100:101]
	v_mov_b32_e32 v236, v149
	v_mov_b32_e32 v237, v149
	s_nop 1
	v_permlane32_swap_b32_e32 v236, v237
	v_cndmask_b32_e64 v151, v237, v236, s[100:101]
	ds_read_b64_tr_b16 v[102:103], v163 offset:0
	ds_read_b64_tr_b16 v[104:105], v163 offset:2560
	ds_read_b64_tr_b16 v[98:99], v163 offset:32
	ds_read_b64_tr_b16 v[100:101], v163 offset:2592
	ds_read_b64_tr_b16 v[94:95], v163 offset:64
	ds_read_b64_tr_b16 v[96:97], v163 offset:2624
	ds_read_b64_tr_b16 v[90:91], v163 offset:96
	ds_read_b64_tr_b16 v[92:93], v163 offset:2656
	s_waitcnt lgkmcnt(0)
	v_cmp_lt_i32_e32 vcc, 0, v156
	s_and_saveexec_b64 s[10:11], vcc
	s_xor_b64 s[10:11], exec, s[10:11]
	s_cbranch_execz .LBB0_588
	v_cmp_ne_u32_e32 vcc, 1, v156
	s_waitcnt lgkmcnt(0)
	v_mov_b64_e32 v[154:155], v[150:151]
	s_and_saveexec_b64 s[12:13], vcc
	v_cndmask_b32_e64 v155, 1.0, v153, s[6:7]
	v_cndmask_b32_e64 v154, 1.0, v152, s[6:7]
	s_or_b64 exec, exec, s[12:13]

; __device__ __forceinline__ unsigned cvt_pk_bf16(float lo, float hi) { unsigned r; asm volatile("v_cvt_pk_bf16_f32 %0, %1, %2" : "=v"(r) : "v"(lo), "v"(hi)); return r; }
; __device__ __forceinline__ f32x4 mfma16(bf16x8 a, bf16x8 b, f32x4 c) { return __builtin_amdgcn_mfma_f32_16x16x32_bf16(a, b, c, 0, 0, 0); }
; template <bool DIAG>
; __device__ __forceinline__ void sb_step(const LAS bf16_t* Kt, unsigned vaddr, int kbase, int qpos, bf16x8 q0, bf16x8 q1, float& carry, f32x4 (&O)[4], int fr, int fq) {
;     ...
;     const f32x2 g = (om[0] * om[1]) * (om[2] * om[3]);
;     f32x2 x1; x1.x = __shfl_xor(g.x, 16); x1.y = __shfl_xor(g.y, 16);
;     const f32x2 p1 = g * x1;
;     f32x2 x2; x2.x = __shfl_xor(p1.x, 32); x2.y = __shfl_xor(p1.y, 32);
;     const f32x2 T = p1 * x2;
;     const f32x2 one = (f32x2){1.0f, 1.0f};
;     const f32x2 hi = fq == 0 ? (x1 * x2) : (fq == 1 ? x2 : (fq == 2 ? x1 : one));
;     f32x2 accv; accv.y = carry * hi.y; accv.x = carry * T.y * hi.x;
;     float a_[2][4];
; #pragma unroll
;     for (int r = 3; r >= 0; --r) { const f32x2 a = sg[r] * accv; accv = accv * om[r]; a_[0][r] = a.x; a_[1][r] = a.y; }
;     carry = carry * T.y * T.x;
;     u32x4 pw; pw.x = cvt_pk_bf16(a_[0][0], a_[0][1]); pw.y = cvt_pk_bf16(a_[0][2], a_[0][3]); pw.z = cvt_pk_bf16(a_[1][0], a_[1][1]); pw.w = cvt_pk_bf16(a_[1][2], a_[1][3]);
;     const bf16x8 pf = __builtin_bit_cast(bf16x8, pw);
; #pragma unroll
;     for (int dt = 0; dt < 4; ++dt) { u32x4 wv; wv.x = vf[dt * 2].x; wv.y = vf[dt * 2].y; wv.z = vf[dt * 2 + 1].x; wv.w = vf[dt * 2 + 1].y; O[dt] = mfma16(__builtin_bit_cast(bf16x8, wv), pf, O[dt]); }
; }
; __device__ __forceinline__ void sb_phase(LAS unsigned char* lds, const bf16_t* P, bf16_t* OB, int G, int cu, int loc) {
;     ...
;                 if (!done) { sb_step<false>(Ks + 32 * AP, vlane + (unsigned)(32 * AP * 2), 64 * kt + 32, qpos, q0, q1, carry, O, fr, fq); done = __all(carry < SB_DONE) != 0; }
;                 if (!done) { sb_step<false>(Ks, vlane, 64 * kt, qpos, q0, q1, carry, O, fr, fq); done = __all(carry < SB_DONE) != 0; }
.LBB0_590:
	s_or_b64 exec, exec, s[10:11]
	s_waitcnt lgkmcnt(0)
	v_pk_mul_f32 v[148:149], v[148:149], v[150:151]
	s_nop 0
	v_mul_f32_e32 v128, v129, v149
	v_pk_mul_f32 v[150:151], v[128:129], v[154:155]
	v_mul_f32_e32 v129, v148, v128
	v_pk_mul_f32 v[146:147], v[146:147], v[150:151]
	v_pk_mul_f32 v[144:145], v[144:145], v[150:151]
	v_pk_mul_f32 v[142:143], v[142:143], v[146:147]
	v_pk_mul_f32 v[138:139], v[138:139], v[146:147]
	v_pk_mul_f32 v[136:137], v[136:137], v[142:143]
	v_pk_mul_f32 v[140:141], v[140:141], v[142:143]
	v_cmp_gt_f32_e32 vcc, s46, v129
	v_pk_mul_f32 v[140:141], v[134:135], v[140:141]
	s_cmp_eq_u64 vcc, exec
	v_cvt_pk_bf16_f32 v134, v140, v136
	v_cvt_pk_bf16_f32 v135, v138, v144
	v_cvt_pk_bf16_f32 v136, v141, v137
	v_cvt_pk_bf16_f32 v137, v139, v145
	s_nop 0
	v_mfma_f32_16x16x32_bf16 v[18:21], v[102:105], v[134:137], v[18:21]
	v_mfma_f32_16x16x32_bf16 v[22:25], v[98:101], v[134:137], v[22:25]
	v_mfma_f32_16x16x32_bf16 v[26:29], v[94:97], v[134:137], v[26:29]
	v_mfma_f32_16x16x32_bf16 v[30:33], v[90:93], v[134:137], v[30:33]
	s_cbranch_scc1 .LBB0_598
	ds_read_b128 v[90:93], v166
	ds_read_b128 v[94:97], v166 offset:64
	ds_read_b128 v[98:101], v166 offset:2560
	ds_read_b128 v[102:105], v166 offset:2624
	v_cmp_lt_i32_e32 vcc, 0, v156
	s_waitcnt lgkmcnt(3)
	v_mfma_f32_16x16x32_bf16 v[90:93], v[90:93], v[62:65], 0
	s_waitcnt lgkmcnt(1)
	v_mfma_f32_16x16x32_bf16 v[98:101], v[98:101], v[62:65], 0
	v_mfma_f32_16x16x32_bf16 v[90:93], v[94:97], v[66:69], v[90:93]
	s_waitcnt lgkmcnt(0)
	v_mfma_f32_16x16x32_bf16 v[94:97], v[102:105], v[66:69], v[98:101]
	s_nop 5
	v_mov_b32_e32 v98, v90
	s_nop 0
	v_mov_b32_e32 v99, v94
	v_mov_b32_e32 v94, v91
	v_pk_mul_f32 v[90:91], v[98:99], s[28:29] op_sel_hi:[1,0]
	v_pk_mul_f32 v[94:95], v[94:95], s[28:29] op_sel_hi:[1,0]
	v_med3_f32 v90, v90, s45, v119
	v_med3_f32 v91, v91, s45, v119
	v_exp_f32_e32 v90, v90
	v_exp_f32_e32 v91, v91
	v_med3_f32 v94, v94, s45, v119
	v_med3_f32 v95, v95, s45, v119
	v_exp_f32_e32 v94, v94
	v_pk_add_f32 v[98:99], v[90:91], 1.0 op_sel_hi:[1,0]
	v_exp_f32_e32 v95, v95
	v_rcp_f32_e32 v134, v98
	v_rcp_f32_e32 v135, v99
	v_mov_b32_e32 v98, v92
	v_mov_b32_e32 v99, v96
	v_pk_mul_f32 v[98:99], v[98:99], s[28:29] op_sel_hi:[1,0]
	v_pk_add_f32 v[100:101], v[94:95], 1.0 op_sel_hi:[1,0]
	v_med3_f32 v96, v99, s45, v119
	v_med3_f32 v92, v98, s45, v119
	v_exp_f32_e32 v99, v96
	v_mov_b32_e32 v96, v93
	v_exp_f32_e32 v98, v92
	v_pk_mul_f32 v[92:93], v[96:97], s[28:29] op_sel_hi:[1,0]
	v_rcp_f32_e32 v136, v100
	v_med3_f32 v92, v92, s45, v119
	v_med3_f32 v93, v93, s45, v119
	v_exp_f32_e32 v92, v92
	v_exp_f32_e32 v93, v93
	v_pk_add_f32 v[96:97], v[98:99], 1.0 op_sel_hi:[1,0]
	v_rcp_f32_e32 v137, v101
	v_rcp_f32_e32 v138, v96
	v_rcp_f32_e32 v139, v97
	v_pk_add_f32 v[96:97], v[92:93], 1.0 op_sel_hi:[1,0]
	v_pk_mul_f32 v[90:91], v[90:91], v[134:135]
	v_rcp_f32_e32 v144, v96
	v_rcp_f32_e32 v145, v97
	v_pk_mul_f32 v[140:141], v[94:95], v[136:137]
	v_pk_mul_f32 v[142:143], v[98:99], v[138:139]
	v_pk_mul_f32 v[90:91], v[90:91], v[140:141]
	v_pk_mul_f32 v[146:147], v[92:93], v[144:145]
	s_nop 0
	v_pk_mul_f32 v[92:93], v[142:143], v[146:147]
	s_nop 0
	v_pk_mul_f32 v[90:91], v[90:91], v[92:93]
	v_mov_b32_e32 v236, v90
	v_mov_b32_e32 v237, v90
	s_nop 1
	v_permlane16_swap_b32_e32 v236, v237
	v_cndmask_b32_e64 v154, v237, v236, s[98:99]
	v_mov_b32_e32 v236, v91
	v_mov_b32_e32 v237, v91
	s_nop 1
	v_permlane16_swap_b32_e32 v236, v237
	v_cndmask_b32_e64 v155, v237, v236, s[98:99]
	s_waitcnt lgkmcnt(0)
	v_pk_mul_f32 v[148:149], v[90:91], v[154:155]
	v_mov_b32_e32 v236, v148
	v_mov_b32_e32 v237, v148
	s_nop 1
	v_permlane32_swap_b32_e32 v236, v237
	v_cndmask_b32_e64 v150, v237, v236, s[100:101]
	v_mov_b32_e32 v236, v149
	v_mov_b32_e32 v237, v149
	s_nop 1
	v_permlane32_swap_b32_e32 v236, v237
	v_cndmask_b32_e64 v151, v237, v236, s[100:101]
	ds_read_b64_tr_b16 v[102:103], v157 offset:0
	ds_read_b64_tr_b16 v[104:105], v157 offset:2560
	ds_read_b64_tr_b16 v[98:99], v157 offset:32
	ds_read_b64_tr_b16 v[100:101], v157 offset:2592
	ds_read_b64_tr_b16 v[94:95], v157 offset:64
	ds_read_b64_tr_b16 v[96:97], v157 offset:2624
	ds_read_b64_tr_b16 v[90:91], v157 offset:96
	ds_read_b64_tr_b16 v[92:93], v157 offset:2656
	s_waitcnt lgkmcnt(0)
	s_and_saveexec_b64 s[10:11], vcc
	s_xor_b64 s[10:11], exec, s[10:11]
	s_cbranch_execz .LBB0_595
	v_cmp_ne_u32_e32 vcc, 1, v156
	s_waitcnt lgkmcnt(0)
	v_mov_b64_e32 v[152:153], v[150:151]
	s_and_saveexec_b64 s[12:13], vcc
	v_cndmask_b32_e64 v153, 1.0, v155, s[6:7]
	v_cndmask_b32_e64 v152, 1.0, v154, s[6:7]
	s_or_b64 exec, exec, s[12:13]
